# peeled first iteration: its first counted vmcnt wait no longer drains the previous tile's epilogue stores (vmcnt 16/20/28 instead of 8 in FFN-up / in-proj / residual copies), on top of the peel
# speedup vs baseline: 1.0032x; 1.0021x over previous
.LBB0_529:
	s_lshl_b32 s10, s30, 8
	s_ashr_i32 s11, s10, 31
	s_lshl_b64 s[10:11], s[10:11], 12
	s_add_u32 s10, s86, s10
	s_addc_u32 s11, s87, s11
	s_and_b64 s[12:13], s[2:3], exec
	s_cselect_b32 s34, s11, s15
	s_cselect_b32 s35, s10, s14
	s_ashr_i32 s9, s8, 31
	s_lshl_b64 s[12:13], s[8:9], 20
	v_readlane_b32 s9, v254, 62
	s_add_u32 s12, s9, s12
	v_readlane_b32 s9, v254, 63
	s_addc_u32 s13, s9, s13
	s_and_b64 s[18:19], s[2:3], exec
	s_cselect_b32 s9, s13, s17
	s_cselect_b32 s36, s12, s16
	s_add_u32 s14, s14, 0x80080
	s_addc_u32 s15, s15, 0
	s_add_u32 s37, s16, 0x100
	s_addc_u32 s38, s17, 0
	s_mov_b32 s39, -2
	s_add_u32 vcc_lo, s14, 0xfff80000
	s_addc_u32 vcc_hi, s15, -1
	s_mov_b32 m0, s27
	s_nop 0
	global_load_lds_dwordx4 v138, vcc
	s_mov_b32 m0, s28
	s_nop 0
	global_load_lds_dwordx4 v140, vcc
	ds_read_b128 v[152:155], v145
	ds_read_b128 v[156:159], v145 offset:1024
	ds_read_b128 v[160:163], v145 offset:2048
	ds_read_b128 v[164:167], v145 offset:3072
	ds_read_b128 v[168:171], v145 offset:16384
	ds_read_b128 v[172:175], v145 offset:17408
	ds_read_b128 v[176:179], v145 offset:18432
	ds_read_b128 v[180:183], v145 offset:19456
	ds_read_b128 v[184:187], v151
	ds_read_b128 v[188:191], v151 offset:1024
	ds_read_b128 v[204:207], v151 offset:2048
	ds_read_b128 v[208:211], v151 offset:3072
	ds_read_b128 v[212:215], v151 offset:4096
	ds_read_b128 v[216:219], v151 offset:5120
	ds_read_b128 v[220:223], v151 offset:6144
	ds_read_b128 v[224:227], v151 offset:7168
	s_add_u32 s16, s14, 0xfff80080
	s_addc_u32 s17, s15, -1
	s_add_i32 s40, 0, 0x10000
	s_cmp_eq_u32 s39, 28
	s_cselect_b32 s19, s34, s17
	s_cselect_b32 s18, s35, s16
	s_cselect_b32 s17, s9, s38
	s_cselect_b32 s16, s36, s37
	s_add_i32 s42, 0, 0x14000
	s_add_i32 m0, s23, 0xc000
	s_nop 0
	global_load_lds_dwordx4 v138, s[14:15]
	s_add_i32 m0, s23, 0xe000
	s_nop 0
	global_load_lds_dwordx4 v140, s[14:15]
	s_waitcnt vmcnt(20)
	s_waitcnt lgkmcnt(0)
	v_mfma_f32_16x16x32_bf16 v[126:129], v[152:155], v[184:187], 0
	v_mfma_f32_16x16x32_bf16 v[126:129], v[156:159], v[188:191], v[126:129]
	s_barrier
	s_setprio 1
	v_mfma_f32_16x16x32_bf16 v[122:125], v[164:167], v[188:191], 0
	v_mfma_f32_16x16x32_bf16 v[122:125], v[160:163], v[184:187], v[122:125]
	v_mfma_f32_16x16x32_bf16 v[106:109], v[160:163], v[204:207], 0
	v_mfma_f32_16x16x32_bf16 v[106:109], v[164:167], v[208:211], v[106:109]
	v_mfma_f32_16x16x32_bf16 v[110:113], v[156:159], v[208:211], 0
	v_mfma_f32_16x16x32_bf16 v[110:113], v[152:155], v[204:207], v[110:113]
	v_mfma_f32_16x16x32_bf16 v[94:97], v[152:155], v[212:215], 0
	v_mfma_f32_16x16x32_bf16 v[94:97], v[156:159], v[216:219], v[94:97]
	v_mfma_f32_16x16x32_bf16 v[90:93], v[164:167], v[216:219], 0
	v_mfma_f32_16x16x32_bf16 v[90:93], v[160:163], v[212:215], v[90:93]
	v_mfma_f32_16x16x32_bf16 v[74:77], v[160:163], v[220:223], 0
	v_mfma_f32_16x16x32_bf16 v[74:77], v[164:167], v[224:227], v[74:77]
	v_mfma_f32_16x16x32_bf16 v[78:81], v[156:159], v[224:227], 0
	v_mfma_f32_16x16x32_bf16 v[78:81], v[152:155], v[220:223], v[78:81]
	v_mfma_f32_16x16x32_bf16 v[118:121], v[168:171], v[184:187], 0
	v_mfma_f32_16x16x32_bf16 v[118:121], v[172:175], v[188:191], v[118:121]
	v_mfma_f32_16x16x32_bf16 v[114:117], v[180:183], v[188:191], 0
	v_mfma_f32_16x16x32_bf16 v[114:117], v[176:179], v[184:187], v[114:117]
	v_mfma_f32_16x16x32_bf16 v[98:101], v[176:179], v[204:207], 0
	v_mfma_f32_16x16x32_bf16 v[98:101], v[180:183], v[208:211], v[98:101]
	v_mfma_f32_16x16x32_bf16 v[102:105], v[172:175], v[208:211], 0
	v_mfma_f32_16x16x32_bf16 v[102:105], v[168:171], v[204:207], v[102:105]
	v_mfma_f32_16x16x32_bf16 v[86:89], v[168:171], v[212:215], 0
	v_mfma_f32_16x16x32_bf16 v[86:89], v[172:175], v[216:219], v[86:89]
	v_mfma_f32_16x16x32_bf16 v[82:85], v[180:183], v[216:219], 0
	v_mfma_f32_16x16x32_bf16 v[82:85], v[176:179], v[212:215], v[82:85]
	v_mfma_f32_16x16x32_bf16 v[66:69], v[176:179], v[220:223], 0
	v_mfma_f32_16x16x32_bf16 v[66:69], v[180:183], v[224:227], v[66:69]
	v_mfma_f32_16x16x32_bf16 v[70:73], v[172:175], v[224:227], 0
	v_mfma_f32_16x16x32_bf16 v[70:73], v[168:171], v[220:223], v[70:73]
	s_setprio 0
	s_barrier
	ds_read_b128 v[184:187], v151 offset:16384
	ds_read_b128 v[188:191], v151 offset:17408
	ds_read_b128 v[204:207], v151 offset:18432
	ds_read_b128 v[208:211], v151 offset:19456
	ds_read_b128 v[212:215], v151 offset:20480
	ds_read_b128 v[216:219], v151 offset:21504
	ds_read_b128 v[220:223], v151 offset:22528
	ds_read_b128 v[224:227], v151 offset:23552
	s_add_i32 s40, s40, s22
	s_mov_b32 m0, s40
	s_nop 0
	global_load_lds_dwordx4 v134, s[16:17]
	s_add_i32 m0, s40, 0x2000
	s_add_u32 s40, s16, 0x80000
	s_addc_u32 s41, s17, 0
	s_add_i32 s42, s42, s22
	global_load_lds_dwordx4 v130, s[16:17]
	s_mov_b32 m0, s42
	s_nop 0
	global_load_lds_dwordx4 v134, s[40:41]
	s_add_i32 m0, s42, 0x2000
	s_nop 0
	global_load_lds_dwordx4 v130, s[40:41]
	s_waitcnt vmcnt(6)
	s_waitcnt lgkmcnt(0)
	v_mfma_f32_16x16x32_bf16 v[62:65], v[152:155], v[184:187], 0
	v_mfma_f32_16x16x32_bf16 v[62:65], v[156:159], v[188:191], v[62:65]
	s_barrier
	s_setprio 1
	v_mfma_f32_16x16x32_bf16 v[58:61], v[164:167], v[188:191], 0
	v_mfma_f32_16x16x32_bf16 v[58:61], v[160:163], v[184:187], v[58:61]
	v_mfma_f32_16x16x32_bf16 v[42:45], v[160:163], v[204:207], 0
	v_mfma_f32_16x16x32_bf16 v[42:45], v[164:167], v[208:211], v[42:45]
	v_mfma_f32_16x16x32_bf16 v[46:49], v[156:159], v[208:211], 0
	v_mfma_f32_16x16x32_bf16 v[46:49], v[152:155], v[204:207], v[46:49]
	v_mfma_f32_16x16x32_bf16 v[30:33], v[152:155], v[212:215], 0
	v_mfma_f32_16x16x32_bf16 v[30:33], v[156:159], v[216:219], v[30:33]
	v_mfma_f32_16x16x32_bf16 v[26:29], v[164:167], v[216:219], 0
	v_mfma_f32_16x16x32_bf16 v[26:29], v[160:163], v[212:215], v[26:29]
	v_mfma_f32_16x16x32_bf16 v[10:13], v[160:163], v[220:223], 0
	v_mfma_f32_16x16x32_bf16 v[10:13], v[164:167], v[224:227], v[10:13]
	v_mfma_f32_16x16x32_bf16 v[14:17], v[156:159], v[224:227], 0
	v_mfma_f32_16x16x32_bf16 v[14:17], v[152:155], v[220:223], v[14:17]
	v_mfma_f32_16x16x32_bf16 v[54:57], v[168:171], v[184:187], 0
	v_mfma_f32_16x16x32_bf16 v[54:57], v[172:175], v[188:191], v[54:57]
	v_mfma_f32_16x16x32_bf16 v[50:53], v[180:183], v[188:191], 0
	v_mfma_f32_16x16x32_bf16 v[50:53], v[176:179], v[184:187], v[50:53]
	v_mfma_f32_16x16x32_bf16 v[34:37], v[176:179], v[204:207], 0
	v_mfma_f32_16x16x32_bf16 v[34:37], v[180:183], v[208:211], v[34:37]
	v_mfma_f32_16x16x32_bf16 v[38:41], v[172:175], v[208:211], 0
	v_mfma_f32_16x16x32_bf16 v[38:41], v[168:171], v[204:207], v[38:41]
	v_mfma_f32_16x16x32_bf16 v[22:25], v[168:171], v[212:215], 0
	v_mfma_f32_16x16x32_bf16 v[22:25], v[172:175], v[216:219], v[22:25]
	v_mfma_f32_16x16x32_bf16 v[18:21], v[180:183], v[216:219], 0
	v_mfma_f32_16x16x32_bf16 v[18:21], v[176:179], v[212:215], v[18:21]
	v_mfma_f32_16x16x32_bf16 v[2:5], v[176:179], v[220:223], 0
	v_mfma_f32_16x16x32_bf16 v[2:5], v[180:183], v[224:227], v[2:5]
	v_mfma_f32_16x16x32_bf16 v[6:9], v[172:175], v[224:227], 0
	v_mfma_f32_16x16x32_bf16 v[6:9], v[168:171], v[220:223], v[6:9]
	s_setprio 0
	s_barrier
	s_mov_b32 m0, s23
	s_nop 0
	global_load_lds_dwordx4 v136, s[18:19]
	s_mov_b32 m0, s24
	s_nop 0
	global_load_lds_dwordx4 v132, s[18:19]
	ds_read_b128 v[152:155], v145 offset:32768
	ds_read_b128 v[156:159], v145 offset:33792
	ds_read_b128 v[160:163], v145 offset:34816
	ds_read_b128 v[164:167], v145 offset:35840
	ds_read_b128 v[168:171], v145 offset:49152
	ds_read_b128 v[172:175], v145 offset:50176
	ds_read_b128 v[176:179], v145 offset:51200
	ds_read_b128 v[180:183], v145 offset:52224
	ds_read_b128 v[184:187], v151 offset:32768
	ds_read_b128 v[188:191], v151 offset:33792
	ds_read_b128 v[204:207], v151 offset:34816
	ds_read_b128 v[208:211], v151 offset:35840
	ds_read_b128 v[212:215], v151 offset:36864
	ds_read_b128 v[216:219], v151 offset:37888
	ds_read_b128 v[220:223], v151 offset:38912
	ds_read_b128 v[224:227], v151 offset:39936
	s_add_i32 s40, 0, 0x18000
	s_add_i32 s41, 0, 0x1c000
	s_add_u32 s18, s18, 0x80000
	s_addc_u32 s19, s19, 0
	s_mov_b32 m0, s25
	s_nop 0
	global_load_lds_dwordx4 v136, s[18:19]
	s_mov_b32 m0, s26
	s_nop 0
	global_load_lds_dwordx4 v132, s[18:19]
	s_waitcnt vmcnt(8)
	s_waitcnt lgkmcnt(0)
	v_mfma_f32_16x16x32_bf16 v[126:129], v[152:155], v[184:187], v[126:129]
	v_mfma_f32_16x16x32_bf16 v[126:129], v[156:159], v[188:191], v[126:129]
	s_barrier
	s_setprio 1
	v_mfma_f32_16x16x32_bf16 v[122:125], v[164:167], v[188:191], v[122:125]
	v_mfma_f32_16x16x32_bf16 v[122:125], v[160:163], v[184:187], v[122:125]
	v_mfma_f32_16x16x32_bf16 v[106:109], v[160:163], v[204:207], v[106:109]
	v_mfma_f32_16x16x32_bf16 v[106:109], v[164:167], v[208:211], v[106:109]
	v_mfma_f32_16x16x32_bf16 v[110:113], v[156:159], v[208:211], v[110:113]
	v_mfma_f32_16x16x32_bf16 v[110:113], v[152:155], v[204:207], v[110:113]
	v_mfma_f32_16x16x32_bf16 v[94:97], v[152:155], v[212:215], v[94:97]
	v_mfma_f32_16x16x32_bf16 v[94:97], v[156:159], v[216:219], v[94:97]
	v_mfma_f32_16x16x32_bf16 v[90:93], v[164:167], v[216:219], v[90:93]
	v_mfma_f32_16x16x32_bf16 v[90:93], v[160:163], v[212:215], v[90:93]
	v_mfma_f32_16x16x32_bf16 v[74:77], v[160:163], v[220:223], v[74:77]
	v_mfma_f32_16x16x32_bf16 v[74:77], v[164:167], v[224:227], v[74:77]
	v_mfma_f32_16x16x32_bf16 v[78:81], v[156:159], v[224:227], v[78:81]
	v_mfma_f32_16x16x32_bf16 v[78:81], v[152:155], v[220:223], v[78:81]
	v_mfma_f32_16x16x32_bf16 v[118:121], v[168:171], v[184:187], v[118:121]
	v_mfma_f32_16x16x32_bf16 v[118:121], v[172:175], v[188:191], v[118:121]
	v_mfma_f32_16x16x32_bf16 v[114:117], v[180:183], v[188:191], v[114:117]
	v_mfma_f32_16x16x32_bf16 v[114:117], v[176:179], v[184:187], v[114:117]
	v_mfma_f32_16x16x32_bf16 v[98:101], v[176:179], v[204:207], v[98:101]
	v_mfma_f32_16x16x32_bf16 v[98:101], v[180:183], v[208:211], v[98:101]
	v_mfma_f32_16x16x32_bf16 v[102:105], v[172:175], v[208:211], v[102:105]
	v_mfma_f32_16x16x32_bf16 v[102:105], v[168:171], v[204:207], v[102:105]
	v_mfma_f32_16x16x32_bf16 v[86:89], v[168:171], v[212:215], v[86:89]
	v_mfma_f32_16x16x32_bf16 v[86:89], v[172:175], v[216:219], v[86:89]
	v_mfma_f32_16x16x32_bf16 v[82:85], v[180:183], v[216:219], v[82:85]
	v_mfma_f32_16x16x32_bf16 v[82:85], v[176:179], v[212:215], v[82:85]
	v_mfma_f32_16x16x32_bf16 v[66:69], v[176:179], v[220:223], v[66:69]
	v_mfma_f32_16x16x32_bf16 v[66:69], v[180:183], v[224:227], v[66:69]
	v_mfma_f32_16x16x32_bf16 v[70:73], v[172:175], v[224:227], v[70:73]
	v_mfma_f32_16x16x32_bf16 v[70:73], v[168:171], v[220:223], v[70:73]
	s_setprio 0
	s_barrier
	ds_read_b128 v[184:187], v151 offset:49152
	ds_read_b128 v[188:191], v151 offset:50176
	ds_read_b128 v[204:207], v151 offset:51200
	ds_read_b128 v[208:211], v151 offset:52224
	ds_read_b128 v[212:215], v151 offset:53248
	ds_read_b128 v[216:219], v151 offset:54272
	ds_read_b128 v[220:223], v151 offset:55296
	ds_read_b128 v[224:227], v151 offset:56320
	s_add_i32 s18, s40, s22
	s_add_u32 vcc_lo, s16, s94
	s_addc_u32 vcc_hi, s17, s95
	s_mov_b32 m0, s18
	s_nop 0
	global_load_lds_dwordx4 v134, vcc
	s_add_i32 m0, s18, 0x2000
	s_add_u32 s16, s16, 0x80080
	s_addc_u32 s17, s17, 0
	s_add_i32 s18, s41, s22
	global_load_lds_dwordx4 v130, vcc
	s_mov_b32 m0, s18
	s_nop 0
	global_load_lds_dwordx4 v134, s[16:17]
	s_add_i32 m0, s18, 0x2000
	s_nop 0
	global_load_lds_dwordx4 v130, s[16:17]
	s_waitcnt vmcnt(6)
	s_waitcnt lgkmcnt(0)
	v_mfma_f32_16x16x32_bf16 v[62:65], v[152:155], v[184:187], v[62:65]
	v_mfma_f32_16x16x32_bf16 v[62:65], v[156:159], v[188:191], v[62:65]
	s_barrier
	s_setprio 1
	v_mfma_f32_16x16x32_bf16 v[58:61], v[164:167], v[188:191], v[58:61]
	v_mfma_f32_16x16x32_bf16 v[58:61], v[160:163], v[184:187], v[58:61]
	v_mfma_f32_16x16x32_bf16 v[42:45], v[160:163], v[204:207], v[42:45]
	v_mfma_f32_16x16x32_bf16 v[42:45], v[164:167], v[208:211], v[42:45]
	v_mfma_f32_16x16x32_bf16 v[46:49], v[156:159], v[208:211], v[46:49]
	v_mfma_f32_16x16x32_bf16 v[46:49], v[152:155], v[204:207], v[46:49]
	v_mfma_f32_16x16x32_bf16 v[30:33], v[152:155], v[212:215], v[30:33]
	v_mfma_f32_16x16x32_bf16 v[30:33], v[156:159], v[216:219], v[30:33]
	v_mfma_f32_16x16x32_bf16 v[26:29], v[164:167], v[216:219], v[26:29]
	v_mfma_f32_16x16x32_bf16 v[26:29], v[160:163], v[212:215], v[26:29]
	v_mfma_f32_16x16x32_bf16 v[10:13], v[160:163], v[220:223], v[10:13]
	v_mfma_f32_16x16x32_bf16 v[10:13], v[164:167], v[224:227], v[10:13]
	s_add_i32 s39, s39, 2
	v_mfma_f32_16x16x32_bf16 v[14:17], v[156:159], v[224:227], v[14:17]
	v_mfma_f32_16x16x32_bf16 v[14:17], v[152:155], v[220:223], v[14:17]
	s_add_u32 s14, s14, 0x100
	v_mfma_f32_16x16x32_bf16 v[54:57], v[168:171], v[184:187], v[54:57]
	v_mfma_f32_16x16x32_bf16 v[54:57], v[172:175], v[188:191], v[54:57]
	s_addc_u32 s15, s15, 0
	v_mfma_f32_16x16x32_bf16 v[50:53], v[180:183], v[188:191], v[50:53]
	v_mfma_f32_16x16x32_bf16 v[50:53], v[176:179], v[184:187], v[50:53]
	s_add_u32 s37, s37, 0x100
	v_mfma_f32_16x16x32_bf16 v[34:37], v[176:179], v[204:207], v[34:37]
	v_mfma_f32_16x16x32_bf16 v[34:37], v[180:183], v[208:211], v[34:37]
	s_addc_u32 s38, s38, 0
	v_mfma_f32_16x16x32_bf16 v[38:41], v[172:175], v[208:211], v[38:41]
	v_mfma_f32_16x16x32_bf16 v[38:41], v[168:171], v[204:207], v[38:41]
	s_cmp_gt_u32 s39, 29
	v_mfma_f32_16x16x32_bf16 v[22:25], v[168:171], v[212:215], v[22:25]
	v_mfma_f32_16x16x32_bf16 v[22:25], v[172:175], v[216:219], v[22:25]
	v_mfma_f32_16x16x32_bf16 v[18:21], v[180:183], v[216:219], v[18:21]
	v_mfma_f32_16x16x32_bf16 v[18:21], v[176:179], v[212:215], v[18:21]
	v_mfma_f32_16x16x32_bf16 v[2:5], v[176:179], v[220:223], v[2:5]
	v_mfma_f32_16x16x32_bf16 v[2:5], v[180:183], v[224:227], v[2:5]
	v_mfma_f32_16x16x32_bf16 v[6:9], v[172:175], v[224:227], v[6:9]
	v_mfma_f32_16x16x32_bf16 v[6:9], v[168:171], v[220:223], v[6:9]
	s_setprio 0
	s_barrier
	s_cbranch_scc1 .Lpeel_exit_2

.LBB0_849:
	s_add_u32 s18, s18, 0x80
	s_addc_u32 s19, s19, 0
	s_add_u32 s51, s20, 0x100
	s_waitcnt lgkmcnt(0)
	s_waitcnt vmcnt(0)
	s_addc_u32 s54, s21, 0
	s_mov_b32 s20, 0
	s_sub_u32 vcc_lo, s18, s12
	s_subb_u32 vcc_hi, s19, 0
	s_mov_b32 m0, s33
	s_nop 0
	global_load_lds_dwordx4 v210, vcc
	s_mov_b32 m0, s34
	s_nop 0
	global_load_lds_dwordx4 v212, vcc
	ds_read_b128 v[66:69], v198
	ds_read_b128 v[78:81], v198 offset:1024
	ds_read_b128 v[82:85], v198 offset:2048
	ds_read_b128 v[98:101], v198 offset:3072
	ds_read_b128 v[106:109], v198 offset:16384
	ds_read_b128 v[118:121], v198 offset:17408
	ds_read_b128 v[130:133], v198 offset:18432
	ds_read_b128 v[142:145], v198 offset:19456
	ds_read_b128 v[150:153], v234
	ds_read_b128 v[154:157], v234 offset:1024
	ds_read_b128 v[158:161], v234 offset:2048
	ds_read_b128 v[162:165], v234 offset:3072
	ds_read_b128 v[170:173], v234 offset:4096
	ds_read_b128 v[174:177], v234 offset:5120
	ds_read_b128 v[178:181], v234 offset:6144
	ds_read_b128 v[190:193], v234 offset:7168
	s_add_i32 s55, s20, 2
	s_add_u32 s56, s18, 0x80
	s_addc_u32 s21, s19, 0
	s_add_i32 s58, 0, 0x10000
	s_cmp_eq_u32 s35, s20
	s_cselect_b32 s21, s1, s21
	s_cselect_b32 s20, s0, s56
	s_cselect_b32 s57, s17, s54
	s_cselect_b32 s56, s16, s51
	s_add_i32 s59, 0, 0x14000
	s_add_i32 m0, s26, 0xc000
	s_nop 0
	global_load_lds_dwordx4 v210, s[18:19]
	s_add_i32 m0, s26, 0xe000
	s_nop 0
	global_load_lds_dwordx4 v212, s[18:19]
	s_waitcnt vmcnt(28)
	s_waitcnt lgkmcnt(0)
	v_mfma_f32_16x16x32_bf16 v[186:189], v[66:69], v[150:153], 0
	v_mfma_f32_16x16x32_bf16 v[186:189], v[78:81], v[154:157], v[186:189]
	s_barrier
	s_setprio 1
	v_mfma_f32_16x16x32_bf16 v[182:185], v[98:101], v[154:157], 0
	v_mfma_f32_16x16x32_bf16 v[182:185], v[82:85], v[150:153], v[182:185]
	v_mfma_f32_16x16x32_bf16 v[134:137], v[82:85], v[158:161], 0
	v_mfma_f32_16x16x32_bf16 v[134:137], v[98:101], v[162:165], v[134:137]
	v_mfma_f32_16x16x32_bf16 v[138:141], v[78:81], v[162:165], 0
	v_mfma_f32_16x16x32_bf16 v[138:141], v[66:69], v[158:161], v[138:141]
	v_mfma_f32_16x16x32_bf16 v[114:117], v[66:69], v[170:173], 0
	v_mfma_f32_16x16x32_bf16 v[114:117], v[78:81], v[174:177], v[114:117]
	v_mfma_f32_16x16x32_bf16 v[110:113], v[98:101], v[174:177], 0
	v_mfma_f32_16x16x32_bf16 v[110:113], v[82:85], v[170:173], v[110:113]
	v_mfma_f32_16x16x32_bf16 v[86:89], v[82:85], v[178:181], 0
	v_mfma_f32_16x16x32_bf16 v[86:89], v[98:101], v[190:193], v[86:89]
	v_mfma_f32_16x16x32_bf16 v[90:93], v[78:81], v[190:193], 0
	v_mfma_f32_16x16x32_bf16 v[90:93], v[66:69], v[178:181], v[90:93]
	v_mfma_f32_16x16x32_bf16 v[166:169], v[106:109], v[150:153], 0
	v_mfma_f32_16x16x32_bf16 v[166:169], v[118:121], v[154:157], v[166:169]
	v_mfma_f32_16x16x32_bf16 v[146:149], v[142:145], v[154:157], 0
	v_mfma_f32_16x16x32_bf16 v[146:149], v[130:133], v[150:153], v[146:149]
	v_mfma_f32_16x16x32_bf16 v[122:125], v[130:133], v[158:161], 0
	v_mfma_f32_16x16x32_bf16 v[122:125], v[142:145], v[162:165], v[122:125]
	v_mfma_f32_16x16x32_bf16 v[126:129], v[118:121], v[162:165], 0
	v_mfma_f32_16x16x32_bf16 v[126:129], v[106:109], v[158:161], v[126:129]
	v_mfma_f32_16x16x32_bf16 v[102:105], v[106:109], v[170:173], 0
	v_mfma_f32_16x16x32_bf16 v[102:105], v[118:121], v[174:177], v[102:105]
	v_mfma_f32_16x16x32_bf16 v[94:97], v[142:145], v[174:177], 0
	v_mfma_f32_16x16x32_bf16 v[94:97], v[130:133], v[170:173], v[94:97]
	v_mfma_f32_16x16x32_bf16 v[70:73], v[130:133], v[178:181], 0
	v_mfma_f32_16x16x32_bf16 v[70:73], v[142:145], v[190:193], v[70:73]
	v_mfma_f32_16x16x32_bf16 v[74:77], v[118:121], v[190:193], 0
	v_mfma_f32_16x16x32_bf16 v[74:77], v[106:109], v[178:181], v[74:77]
	s_setprio 0
	s_barrier
	ds_read_b128 v[150:153], v234 offset:16384
	ds_read_b128 v[154:157], v234 offset:17408
	ds_read_b128 v[158:161], v234 offset:18432
	ds_read_b128 v[162:165], v234 offset:19456
	ds_read_b128 v[170:173], v234 offset:20480
	ds_read_b128 v[174:177], v234 offset:21504
	ds_read_b128 v[178:181], v234 offset:22528
	ds_read_b128 v[190:193], v234 offset:23552
	s_add_i32 s58, s58, s24
	v_lshl_add_u64 v[214:215], s[56:57], 0, v[194:195]
	s_mov_b32 m0, s58
	s_nop 0
	global_load_lds_dwordx4 v194, s[56:57]
	s_add_i32 m0, s58, 0x2000
	v_lshl_add_u64 v[216:217], s[56:57], 0, v[204:205]
	s_add_u32 s56, s56, s12
	s_addc_u32 s57, s57, 0
	s_add_i32 s58, s59, s24
	global_load_lds_dwordx4 v[216:217], off
	v_lshl_add_u64 v[218:219], s[56:57], 0, v[194:195]
	s_mov_b32 m0, s58
	v_lshl_add_u64 v[220:221], s[56:57], 0, v[204:205]
	global_load_lds_dwordx4 v194, s[56:57]
	s_add_i32 m0, s58, 0x2000
	s_nop 0
	global_load_lds_dwordx4 v204, s[56:57]
	s_waitcnt vmcnt(6)
	s_waitcnt lgkmcnt(0)
	v_mfma_f32_16x16x32_bf16 v[62:65], v[66:69], v[150:153], 0
	v_mfma_f32_16x16x32_bf16 v[62:65], v[78:81], v[154:157], v[62:65]
	s_barrier
	s_setprio 1
	v_mfma_f32_16x16x32_bf16 v[58:61], v[98:101], v[154:157], 0
	v_mfma_f32_16x16x32_bf16 v[58:61], v[82:85], v[150:153], v[58:61]
	v_mfma_f32_16x16x32_bf16 v[42:45], v[82:85], v[158:161], 0
	v_mfma_f32_16x16x32_bf16 v[42:45], v[98:101], v[162:165], v[42:45]
	v_mfma_f32_16x16x32_bf16 v[46:49], v[78:81], v[162:165], 0
	v_mfma_f32_16x16x32_bf16 v[46:49], v[66:69], v[158:161], v[46:49]
	v_mfma_f32_16x16x32_bf16 v[30:33], v[66:69], v[170:173], 0
	v_mfma_f32_16x16x32_bf16 v[30:33], v[78:81], v[174:177], v[30:33]
	v_mfma_f32_16x16x32_bf16 v[26:29], v[98:101], v[174:177], 0
	v_mfma_f32_16x16x32_bf16 v[26:29], v[82:85], v[170:173], v[26:29]
	v_mfma_f32_16x16x32_bf16 v[10:13], v[82:85], v[178:181], 0
	v_mfma_f32_16x16x32_bf16 v[10:13], v[98:101], v[190:193], v[10:13]
	v_mfma_f32_16x16x32_bf16 v[14:17], v[78:81], v[190:193], 0
	v_mfma_f32_16x16x32_bf16 v[14:17], v[66:69], v[178:181], v[14:17]
	v_mfma_f32_16x16x32_bf16 v[54:57], v[106:109], v[150:153], 0
	v_mfma_f32_16x16x32_bf16 v[54:57], v[118:121], v[154:157], v[54:57]
	v_mfma_f32_16x16x32_bf16 v[50:53], v[142:145], v[154:157], 0
	v_mfma_f32_16x16x32_bf16 v[50:53], v[130:133], v[150:153], v[50:53]
	v_mfma_f32_16x16x32_bf16 v[34:37], v[130:133], v[158:161], 0
	v_mfma_f32_16x16x32_bf16 v[34:37], v[142:145], v[162:165], v[34:37]
	v_mfma_f32_16x16x32_bf16 v[38:41], v[118:121], v[162:165], 0
	v_mfma_f32_16x16x32_bf16 v[38:41], v[106:109], v[158:161], v[38:41]
	v_mfma_f32_16x16x32_bf16 v[22:25], v[106:109], v[170:173], 0
	v_mfma_f32_16x16x32_bf16 v[22:25], v[118:121], v[174:177], v[22:25]
	v_mfma_f32_16x16x32_bf16 v[18:21], v[142:145], v[174:177], 0
	v_mfma_f32_16x16x32_bf16 v[18:21], v[130:133], v[170:173], v[18:21]
	v_mfma_f32_16x16x32_bf16 v[2:5], v[130:133], v[178:181], 0
	v_mfma_f32_16x16x32_bf16 v[2:5], v[142:145], v[190:193], v[2:5]
	v_mfma_f32_16x16x32_bf16 v[6:9], v[118:121], v[190:193], 0
	v_mfma_f32_16x16x32_bf16 v[6:9], v[106:109], v[178:181], v[6:9]
	s_setprio 0
	s_barrier
	s_mov_b32 m0, s26
	s_nop 0
	global_load_lds_dwordx4 v208, s[20:21]
	s_mov_b32 m0, s27
	s_nop 0
	global_load_lds_dwordx4 v206, s[20:21]
	ds_read_b128 v[66:69], v198 offset:32768
	ds_read_b128 v[78:81], v198 offset:33792
	ds_read_b128 v[82:85], v198 offset:34816
	ds_read_b128 v[98:101], v198 offset:35840
	ds_read_b128 v[106:109], v198 offset:49152
	ds_read_b128 v[118:121], v198 offset:50176
	ds_read_b128 v[130:133], v198 offset:51200
	ds_read_b128 v[142:145], v198 offset:52224
	ds_read_b128 v[150:153], v234 offset:32768
	ds_read_b128 v[154:157], v234 offset:33792
	ds_read_b128 v[158:161], v234 offset:34816
	ds_read_b128 v[162:165], v234 offset:35840
	ds_read_b128 v[170:173], v234 offset:36864
	ds_read_b128 v[174:177], v234 offset:37888
	ds_read_b128 v[178:181], v234 offset:38912
	ds_read_b128 v[190:193], v234 offset:39936
	s_add_i32 s56, 0, 0x18000
	s_add_i32 s57, 0, 0x1c000
	s_add_u32 s20, s20, s12
	s_addc_u32 s21, s21, 0
	s_mov_b32 m0, s28
	s_nop 0
	global_load_lds_dwordx4 v208, s[20:21]
	s_mov_b32 m0, s29
	s_nop 0
	global_load_lds_dwordx4 v206, s[20:21]
	s_waitcnt vmcnt(8)
	s_waitcnt lgkmcnt(0)
	v_mfma_f32_16x16x32_bf16 v[186:189], v[66:69], v[150:153], v[186:189]
	v_mfma_f32_16x16x32_bf16 v[186:189], v[78:81], v[154:157], v[186:189]
	s_barrier
	s_setprio 1
	v_mfma_f32_16x16x32_bf16 v[182:185], v[98:101], v[154:157], v[182:185]
	v_mfma_f32_16x16x32_bf16 v[182:185], v[82:85], v[150:153], v[182:185]
	v_mfma_f32_16x16x32_bf16 v[134:137], v[82:85], v[158:161], v[134:137]
	v_mfma_f32_16x16x32_bf16 v[134:137], v[98:101], v[162:165], v[134:137]
	v_mfma_f32_16x16x32_bf16 v[138:141], v[78:81], v[162:165], v[138:141]
	v_mfma_f32_16x16x32_bf16 v[138:141], v[66:69], v[158:161], v[138:141]
	v_mfma_f32_16x16x32_bf16 v[114:117], v[66:69], v[170:173], v[114:117]
	v_mfma_f32_16x16x32_bf16 v[114:117], v[78:81], v[174:177], v[114:117]
	v_mfma_f32_16x16x32_bf16 v[110:113], v[98:101], v[174:177], v[110:113]
	v_mfma_f32_16x16x32_bf16 v[110:113], v[82:85], v[170:173], v[110:113]
	v_mfma_f32_16x16x32_bf16 v[86:89], v[82:85], v[178:181], v[86:89]
	v_mfma_f32_16x16x32_bf16 v[86:89], v[98:101], v[190:193], v[86:89]
	v_mfma_f32_16x16x32_bf16 v[90:93], v[78:81], v[190:193], v[90:93]
	v_mfma_f32_16x16x32_bf16 v[90:93], v[66:69], v[178:181], v[90:93]
	v_mfma_f32_16x16x32_bf16 v[166:169], v[106:109], v[150:153], v[166:169]
	v_mfma_f32_16x16x32_bf16 v[166:169], v[118:121], v[154:157], v[166:169]
	v_mfma_f32_16x16x32_bf16 v[146:149], v[142:145], v[154:157], v[146:149]
	v_mfma_f32_16x16x32_bf16 v[146:149], v[130:133], v[150:153], v[146:149]
	v_mfma_f32_16x16x32_bf16 v[122:125], v[130:133], v[158:161], v[122:125]
	v_mfma_f32_16x16x32_bf16 v[122:125], v[142:145], v[162:165], v[122:125]
	v_mfma_f32_16x16x32_bf16 v[126:129], v[118:121], v[162:165], v[126:129]
	v_mfma_f32_16x16x32_bf16 v[126:129], v[106:109], v[158:161], v[126:129]
	v_mfma_f32_16x16x32_bf16 v[102:105], v[106:109], v[170:173], v[102:105]
	v_mfma_f32_16x16x32_bf16 v[102:105], v[118:121], v[174:177], v[102:105]
	v_mfma_f32_16x16x32_bf16 v[94:97], v[142:145], v[174:177], v[94:97]
	v_mfma_f32_16x16x32_bf16 v[94:97], v[130:133], v[170:173], v[94:97]
	v_mfma_f32_16x16x32_bf16 v[70:73], v[130:133], v[178:181], v[70:73]
	v_mfma_f32_16x16x32_bf16 v[70:73], v[142:145], v[190:193], v[70:73]
	v_mfma_f32_16x16x32_bf16 v[74:77], v[118:121], v[190:193], v[74:77]
	v_mfma_f32_16x16x32_bf16 v[74:77], v[106:109], v[178:181], v[74:77]
	s_setprio 0
	s_barrier
	ds_read_b128 v[150:153], v234 offset:49152
	ds_read_b128 v[154:157], v234 offset:50176
	ds_read_b128 v[158:161], v234 offset:51200
	ds_read_b128 v[162:165], v234 offset:52224
	ds_read_b128 v[170:173], v234 offset:53248
	ds_read_b128 v[174:177], v234 offset:54272
	ds_read_b128 v[178:181], v234 offset:55296
	ds_read_b128 v[190:193], v234 offset:56320
	s_add_i32 s20, s56, s24
	v_lshl_add_u64 v[214:215], v[214:215], 0, s[94:95]
	s_mov_b32 m0, s20
	s_nop 0
	global_load_lds_dwordx4 v[214:215], off
	v_lshl_add_u64 v[214:215], v[216:217], 0, s[94:95]
	s_add_i32 m0, s20, 0x2000
	s_add_i32 s20, s57, s24
	global_load_lds_dwordx4 v[214:215], off
	v_lshl_add_u64 v[214:215], v[218:219], 0, s[94:95]
	s_mov_b32 m0, s20
	s_nop 0
	global_load_lds_dwordx4 v[214:215], off
	v_lshl_add_u64 v[214:215], v[220:221], 0, s[94:95]
	s_add_i32 m0, s20, 0x2000
	s_nop 0
	global_load_lds_dwordx4 v[214:215], off
	s_waitcnt vmcnt(6)
	s_waitcnt lgkmcnt(0)
	v_mfma_f32_16x16x32_bf16 v[62:65], v[66:69], v[150:153], v[62:65]
	v_mfma_f32_16x16x32_bf16 v[62:65], v[78:81], v[154:157], v[62:65]
	s_barrier
	s_setprio 1
	v_mfma_f32_16x16x32_bf16 v[58:61], v[98:101], v[154:157], v[58:61]
	v_mfma_f32_16x16x32_bf16 v[58:61], v[82:85], v[150:153], v[58:61]
	v_mfma_f32_16x16x32_bf16 v[42:45], v[82:85], v[158:161], v[42:45]
	v_mfma_f32_16x16x32_bf16 v[42:45], v[98:101], v[162:165], v[42:45]
	v_mfma_f32_16x16x32_bf16 v[46:49], v[78:81], v[162:165], v[46:49]
	v_mfma_f32_16x16x32_bf16 v[46:49], v[66:69], v[158:161], v[46:49]
	v_mfma_f32_16x16x32_bf16 v[30:33], v[66:69], v[170:173], v[30:33]
	v_mfma_f32_16x16x32_bf16 v[30:33], v[78:81], v[174:177], v[30:33]
	v_mfma_f32_16x16x32_bf16 v[26:29], v[98:101], v[174:177], v[26:29]
	v_mfma_f32_16x16x32_bf16 v[26:29], v[82:85], v[170:173], v[26:29]
	v_mfma_f32_16x16x32_bf16 v[10:13], v[82:85], v[178:181], v[10:13]
	v_mfma_f32_16x16x32_bf16 v[10:13], v[98:101], v[190:193], v[10:13]
	s_add_u32 s18, s18, 0x100
	v_mfma_f32_16x16x32_bf16 v[14:17], v[78:81], v[190:193], v[14:17]
	v_mfma_f32_16x16x32_bf16 v[14:17], v[66:69], v[178:181], v[14:17]
	s_addc_u32 s19, s19, 0
	v_mfma_f32_16x16x32_bf16 v[54:57], v[106:109], v[150:153], v[54:57]
	v_mfma_f32_16x16x32_bf16 v[54:57], v[118:121], v[154:157], v[54:57]
	s_add_u32 s51, s51, 0x100
	v_mfma_f32_16x16x32_bf16 v[50:53], v[142:145], v[154:157], v[50:53]
	v_mfma_f32_16x16x32_bf16 v[50:53], v[130:133], v[150:153], v[50:53]
	s_addc_u32 s54, s54, 0
	v_mfma_f32_16x16x32_bf16 v[34:37], v[130:133], v[158:161], v[34:37]
	v_mfma_f32_16x16x32_bf16 v[34:37], v[142:145], v[162:165], v[34:37]
	s_cmp_ge_u32 s55, s53
	v_mfma_f32_16x16x32_bf16 v[38:41], v[118:121], v[162:165], v[38:41]
	v_mfma_f32_16x16x32_bf16 v[38:41], v[106:109], v[158:161], v[38:41]
	s_mov_b32 s20, s55
	v_mfma_f32_16x16x32_bf16 v[22:25], v[106:109], v[170:173], v[22:25]
	v_mfma_f32_16x16x32_bf16 v[22:25], v[118:121], v[174:177], v[22:25]
	v_mfma_f32_16x16x32_bf16 v[18:21], v[142:145], v[174:177], v[18:21]
	v_mfma_f32_16x16x32_bf16 v[18:21], v[130:133], v[170:173], v[18:21]
	v_mfma_f32_16x16x32_bf16 v[2:5], v[130:133], v[178:181], v[2:5]
	v_mfma_f32_16x16x32_bf16 v[2:5], v[142:145], v[190:193], v[2:5]
	v_mfma_f32_16x16x32_bf16 v[6:9], v[118:121], v[190:193], v[6:9]
	v_mfma_f32_16x16x32_bf16 v[6:9], v[106:109], v[178:181], v[6:9]
	s_setprio 0
	s_barrier
	s_cbranch_scc1 .Lpeel_exit_5

.LBB0_972:
	s_ashr_i32 s29, s28, 31
	s_lshl_b64 s[10:11], s[28:29], 20
	s_add_u32 s36, s46, s10
	s_addc_u32 s37, s47, s11
	s_and_b64 s[4:5], s[4:5], exec
	s_cselect_b32 s13, s37, s7
	s_cselect_b32 s29, s36, s6
	s_add_u32 s33, s6, 0x100
	s_addc_u32 s38, s7, 0
	s_mov_b32 s39, -2
	s_add_u32 vcc_lo, s0, 0xffffc000
	s_addc_u32 vcc_hi, s1, -1
	s_mov_b32 m0, s59
	s_nop 0
	global_load_lds_dwordx4 v146, vcc
	s_mov_b32 m0, s60
	s_nop 0
	global_load_lds_dwordx4 v148, vcc
	ds_read_b128 v[130:133], v246
	ds_read_b128 v[134:137], v246 offset:1024
	ds_read_b128 v[150:153], v246 offset:2048
	ds_read_b128 v[154:157], v246 offset:3072
	ds_read_b128 v[158:161], v246 offset:16384
	ds_read_b128 v[162:165], v246 offset:17408
	ds_read_b128 v[166:169], v246 offset:18432
	ds_read_b128 v[170:173], v246 offset:19456
	ds_read_b128 v[174:177], v247
	ds_read_b128 v[178:181], v247 offset:1024
	ds_read_b128 v[182:185], v247 offset:2048
	ds_read_b128 v[186:189], v247 offset:3072
	ds_read_b128 v[190:193], v247 offset:4096
	ds_read_b128 v[204:207], v247 offset:5120
	ds_read_b128 v[208:211], v247 offset:6144
	ds_read_b128 v[212:215], v247 offset:7168
	s_add_u32 s4, s0, 0x100
	s_addc_u32 s5, s1, 0
	s_add_i32 s40, 0, 0x10000
	s_cmp_eq_u32 s39, 28
	s_cselect_b32 s11, s35, s5
	s_cselect_b32 s10, s34, s4
	s_cselect_b32 s7, s13, s38
	s_cselect_b32 s6, s29, s33
	s_add_i32 s41, 0, 0x14000
	s_add_i32 m0, s49, 0xc000
	s_nop 0
	global_load_lds_dwordx4 v146, s[0:1]
	s_add_i32 m0, s49, 0xe000
	s_nop 0
	global_load_lds_dwordx4 v148, s[0:1]
	s_waitcnt vmcnt(16)
	s_waitcnt lgkmcnt(0)
	v_mfma_f32_16x16x32_bf16 v[126:129], v[130:133], v[174:177], 0
	v_mfma_f32_16x16x32_bf16 v[126:129], v[134:137], v[178:181], v[126:129]
	s_barrier
	s_setprio 1
	v_mfma_f32_16x16x32_bf16 v[62:65], v[154:157], v[178:181], 0
	v_mfma_f32_16x16x32_bf16 v[62:65], v[150:153], v[174:177], v[62:65]
	v_mfma_f32_16x16x32_bf16 v[58:61], v[150:153], v[182:185], 0
	v_mfma_f32_16x16x32_bf16 v[58:61], v[154:157], v[186:189], v[58:61]
	v_mfma_f32_16x16x32_bf16 v[122:125], v[134:137], v[186:189], 0
	v_mfma_f32_16x16x32_bf16 v[122:125], v[130:133], v[182:185], v[122:125]
	v_mfma_f32_16x16x32_bf16 v[114:117], v[130:133], v[190:193], 0
	v_mfma_f32_16x16x32_bf16 v[114:117], v[134:137], v[204:207], v[114:117]
	v_mfma_f32_16x16x32_bf16 v[50:53], v[154:157], v[204:207], 0
	v_mfma_f32_16x16x32_bf16 v[50:53], v[150:153], v[190:193], v[50:53]
	v_mfma_f32_16x16x32_bf16 v[42:45], v[150:153], v[208:211], 0
	v_mfma_f32_16x16x32_bf16 v[42:45], v[154:157], v[212:215], v[42:45]
	v_mfma_f32_16x16x32_bf16 v[106:109], v[134:137], v[212:215], 0
	v_mfma_f32_16x16x32_bf16 v[106:109], v[130:133], v[208:211], v[106:109]
	v_mfma_f32_16x16x32_bf16 v[118:121], v[158:161], v[174:177], 0
	v_mfma_f32_16x16x32_bf16 v[118:121], v[162:165], v[178:181], v[118:121]
	v_mfma_f32_16x16x32_bf16 v[54:57], v[170:173], v[178:181], 0
	v_mfma_f32_16x16x32_bf16 v[54:57], v[166:169], v[174:177], v[54:57]
	v_mfma_f32_16x16x32_bf16 v[46:49], v[166:169], v[182:185], 0
	v_mfma_f32_16x16x32_bf16 v[46:49], v[170:173], v[186:189], v[46:49]
	v_mfma_f32_16x16x32_bf16 v[110:113], v[162:165], v[186:189], 0
	v_mfma_f32_16x16x32_bf16 v[110:113], v[158:161], v[182:185], v[110:113]
	v_mfma_f32_16x16x32_bf16 v[102:105], v[158:161], v[190:193], 0
	v_mfma_f32_16x16x32_bf16 v[102:105], v[162:165], v[204:207], v[102:105]
	v_mfma_f32_16x16x32_bf16 v[38:41], v[170:173], v[204:207], 0
	v_mfma_f32_16x16x32_bf16 v[38:41], v[166:169], v[190:193], v[38:41]
	v_mfma_f32_16x16x32_bf16 v[34:37], v[166:169], v[208:211], 0
	v_mfma_f32_16x16x32_bf16 v[34:37], v[170:173], v[212:215], v[34:37]
	v_mfma_f32_16x16x32_bf16 v[98:101], v[162:165], v[212:215], 0
	v_mfma_f32_16x16x32_bf16 v[98:101], v[158:161], v[208:211], v[98:101]
	s_setprio 0
	s_barrier
	ds_read_b128 v[174:177], v247 offset:16384
	ds_read_b128 v[178:181], v247 offset:17408
	ds_read_b128 v[182:185], v247 offset:18432
	ds_read_b128 v[186:189], v247 offset:19456
	ds_read_b128 v[190:193], v247 offset:20480
	ds_read_b128 v[204:207], v247 offset:21504
	ds_read_b128 v[208:211], v247 offset:22528
	ds_read_b128 v[212:215], v247 offset:23552
	s_add_i32 s0, s40, s48
	s_mov_b32 m0, s0
	s_nop 0
	global_load_lds_dwordx4 v140, s[6:7]
	s_add_i32 m0, s0, 0x2000
	s_add_u32 s0, s6, 0x80000
	s_addc_u32 s1, s7, 0
	s_add_i32 s40, s41, s48
	global_load_lds_dwordx4 v144, s[6:7]
	s_mov_b32 m0, s40
	s_nop 0
	global_load_lds_dwordx4 v140, s[0:1]
	s_add_i32 m0, s40, 0x2000
	s_nop 0
	global_load_lds_dwordx4 v144, s[0:1]
	s_waitcnt vmcnt(6)
	s_waitcnt lgkmcnt(0)
	v_mfma_f32_16x16x32_bf16 v[94:97], v[130:133], v[174:177], 0
	v_mfma_f32_16x16x32_bf16 v[94:97], v[134:137], v[178:181], v[94:97]
	s_barrier
	s_setprio 1
	v_mfma_f32_16x16x32_bf16 v[30:33], v[154:157], v[178:181], 0
	v_mfma_f32_16x16x32_bf16 v[30:33], v[150:153], v[174:177], v[30:33]
	v_mfma_f32_16x16x32_bf16 v[26:29], v[150:153], v[182:185], 0
	v_mfma_f32_16x16x32_bf16 v[26:29], v[154:157], v[186:189], v[26:29]
	v_mfma_f32_16x16x32_bf16 v[90:93], v[134:137], v[186:189], 0
	v_mfma_f32_16x16x32_bf16 v[90:93], v[130:133], v[182:185], v[90:93]
	v_mfma_f32_16x16x32_bf16 v[82:85], v[130:133], v[190:193], 0
	v_mfma_f32_16x16x32_bf16 v[82:85], v[134:137], v[204:207], v[82:85]
	v_mfma_f32_16x16x32_bf16 v[18:21], v[154:157], v[204:207], 0
	v_mfma_f32_16x16x32_bf16 v[18:21], v[150:153], v[190:193], v[18:21]
	v_mfma_f32_16x16x32_bf16 v[10:13], v[150:153], v[208:211], 0
	v_mfma_f32_16x16x32_bf16 v[10:13], v[154:157], v[212:215], v[10:13]
	v_mfma_f32_16x16x32_bf16 v[74:77], v[134:137], v[212:215], 0
	v_mfma_f32_16x16x32_bf16 v[74:77], v[130:133], v[208:211], v[74:77]
	v_mfma_f32_16x16x32_bf16 v[86:89], v[158:161], v[174:177], 0
	v_mfma_f32_16x16x32_bf16 v[86:89], v[162:165], v[178:181], v[86:89]
	v_mfma_f32_16x16x32_bf16 v[22:25], v[170:173], v[178:181], 0
	v_mfma_f32_16x16x32_bf16 v[22:25], v[166:169], v[174:177], v[22:25]
	v_mfma_f32_16x16x32_bf16 v[14:17], v[166:169], v[182:185], 0
	v_mfma_f32_16x16x32_bf16 v[14:17], v[170:173], v[186:189], v[14:17]
	v_mfma_f32_16x16x32_bf16 v[78:81], v[162:165], v[186:189], 0
	v_mfma_f32_16x16x32_bf16 v[78:81], v[158:161], v[182:185], v[78:81]
	v_mfma_f32_16x16x32_bf16 v[70:73], v[158:161], v[190:193], 0
	v_mfma_f32_16x16x32_bf16 v[70:73], v[162:165], v[204:207], v[70:73]
	v_mfma_f32_16x16x32_bf16 v[6:9], v[170:173], v[204:207], 0
	v_mfma_f32_16x16x32_bf16 v[6:9], v[166:169], v[190:193], v[6:9]
	v_mfma_f32_16x16x32_bf16 v[2:5], v[166:169], v[208:211], 0
	v_mfma_f32_16x16x32_bf16 v[2:5], v[170:173], v[212:215], v[2:5]
	v_mfma_f32_16x16x32_bf16 v[66:69], v[162:165], v[212:215], 0
	v_mfma_f32_16x16x32_bf16 v[66:69], v[158:161], v[208:211], v[66:69]
	s_setprio 0
	s_barrier
	s_mov_b32 m0, s49
	s_nop 0
	global_load_lds_dwordx4 v138, s[10:11]
	s_mov_b32 m0, s70
	s_nop 0
	global_load_lds_dwordx4 v142, s[10:11]
	ds_read_b128 v[130:133], v246 offset:32768
	ds_read_b128 v[134:137], v246 offset:33792
	ds_read_b128 v[150:153], v246 offset:34816
	ds_read_b128 v[154:157], v246 offset:35840
	ds_read_b128 v[158:161], v246 offset:49152
	ds_read_b128 v[162:165], v246 offset:50176
	ds_read_b128 v[166:169], v246 offset:51200
	ds_read_b128 v[170:173], v246 offset:52224
	ds_read_b128 v[174:177], v247 offset:32768
	ds_read_b128 v[178:181], v247 offset:33792
	ds_read_b128 v[182:185], v247 offset:34816
	ds_read_b128 v[186:189], v247 offset:35840
	ds_read_b128 v[190:193], v247 offset:36864
	ds_read_b128 v[204:207], v247 offset:37888
	ds_read_b128 v[208:211], v247 offset:38912
	ds_read_b128 v[212:215], v247 offset:39936
	s_add_i32 s40, 0, 0x18000
	s_add_i32 s41, 0, 0x1c000
	s_add_u32 s0, s10, 0x4000
	s_addc_u32 s1, s11, 0
	s_mov_b32 m0, s71
	s_nop 0
	global_load_lds_dwordx4 v138, s[0:1]
	s_mov_b32 m0, s73
	s_nop 0
	global_load_lds_dwordx4 v142, s[0:1]
	s_waitcnt vmcnt(8)
	s_waitcnt lgkmcnt(0)
	v_mfma_f32_16x16x32_bf16 v[126:129], v[130:133], v[174:177], v[126:129]
	v_mfma_f32_16x16x32_bf16 v[126:129], v[134:137], v[178:181], v[126:129]
	s_barrier
	s_setprio 1
	v_mfma_f32_16x16x32_bf16 v[62:65], v[154:157], v[178:181], v[62:65]
	v_mfma_f32_16x16x32_bf16 v[62:65], v[150:153], v[174:177], v[62:65]
	v_mfma_f32_16x16x32_bf16 v[58:61], v[150:153], v[182:185], v[58:61]
	v_mfma_f32_16x16x32_bf16 v[58:61], v[154:157], v[186:189], v[58:61]
	v_mfma_f32_16x16x32_bf16 v[122:125], v[134:137], v[186:189], v[122:125]
	v_mfma_f32_16x16x32_bf16 v[122:125], v[130:133], v[182:185], v[122:125]
	v_mfma_f32_16x16x32_bf16 v[114:117], v[130:133], v[190:193], v[114:117]
	v_mfma_f32_16x16x32_bf16 v[114:117], v[134:137], v[204:207], v[114:117]
	v_mfma_f32_16x16x32_bf16 v[50:53], v[154:157], v[204:207], v[50:53]
	v_mfma_f32_16x16x32_bf16 v[50:53], v[150:153], v[190:193], v[50:53]
	v_mfma_f32_16x16x32_bf16 v[42:45], v[150:153], v[208:211], v[42:45]
	v_mfma_f32_16x16x32_bf16 v[42:45], v[154:157], v[212:215], v[42:45]
	v_mfma_f32_16x16x32_bf16 v[106:109], v[134:137], v[212:215], v[106:109]
	v_mfma_f32_16x16x32_bf16 v[106:109], v[130:133], v[208:211], v[106:109]
	v_mfma_f32_16x16x32_bf16 v[118:121], v[158:161], v[174:177], v[118:121]
	v_mfma_f32_16x16x32_bf16 v[118:121], v[162:165], v[178:181], v[118:121]
	v_mfma_f32_16x16x32_bf16 v[54:57], v[170:173], v[178:181], v[54:57]
	v_mfma_f32_16x16x32_bf16 v[54:57], v[166:169], v[174:177], v[54:57]
	v_mfma_f32_16x16x32_bf16 v[46:49], v[166:169], v[182:185], v[46:49]
	v_mfma_f32_16x16x32_bf16 v[46:49], v[170:173], v[186:189], v[46:49]
	v_mfma_f32_16x16x32_bf16 v[110:113], v[162:165], v[186:189], v[110:113]
	v_mfma_f32_16x16x32_bf16 v[110:113], v[158:161], v[182:185], v[110:113]
	v_mfma_f32_16x16x32_bf16 v[102:105], v[158:161], v[190:193], v[102:105]
	v_mfma_f32_16x16x32_bf16 v[102:105], v[162:165], v[204:207], v[102:105]
	v_mfma_f32_16x16x32_bf16 v[38:41], v[170:173], v[204:207], v[38:41]
	v_mfma_f32_16x16x32_bf16 v[38:41], v[166:169], v[190:193], v[38:41]
	v_mfma_f32_16x16x32_bf16 v[34:37], v[166:169], v[208:211], v[34:37]
	v_mfma_f32_16x16x32_bf16 v[34:37], v[170:173], v[212:215], v[34:37]
	v_mfma_f32_16x16x32_bf16 v[98:101], v[162:165], v[212:215], v[98:101]
	v_mfma_f32_16x16x32_bf16 v[98:101], v[158:161], v[208:211], v[98:101]
	s_setprio 0
	s_barrier
	ds_read_b128 v[174:177], v247 offset:49152
	ds_read_b128 v[178:181], v247 offset:50176
	ds_read_b128 v[182:185], v247 offset:51200
	ds_read_b128 v[186:189], v247 offset:52224
	ds_read_b128 v[190:193], v247 offset:53248
	ds_read_b128 v[204:207], v247 offset:54272
	ds_read_b128 v[208:211], v247 offset:55296
	ds_read_b128 v[212:215], v247 offset:56320
	s_add_i32 s0, s40, s48
	s_add_u32 vcc_lo, s6, s94
	s_addc_u32 vcc_hi, s7, s95
	s_mov_b32 m0, s0
	s_nop 0
	global_load_lds_dwordx4 v140, vcc
	s_add_i32 m0, s0, 0x2000
	s_add_u32 s0, s6, 0x80080
	s_addc_u32 s1, s7, 0
	s_add_i32 s6, s41, s48
	global_load_lds_dwordx4 v144, vcc
	s_mov_b32 m0, s6
	s_nop 0
	global_load_lds_dwordx4 v140, s[0:1]
	s_add_i32 m0, s6, 0x2000
	s_nop 0
	global_load_lds_dwordx4 v144, s[0:1]
	s_waitcnt vmcnt(6)
	s_waitcnt lgkmcnt(0)
	v_mfma_f32_16x16x32_bf16 v[94:97], v[130:133], v[174:177], v[94:97]
	v_mfma_f32_16x16x32_bf16 v[94:97], v[134:137], v[178:181], v[94:97]
	s_barrier
	s_setprio 1
	v_mfma_f32_16x16x32_bf16 v[30:33], v[154:157], v[178:181], v[30:33]
	v_mfma_f32_16x16x32_bf16 v[30:33], v[150:153], v[174:177], v[30:33]
	v_mfma_f32_16x16x32_bf16 v[26:29], v[150:153], v[182:185], v[26:29]
	v_mfma_f32_16x16x32_bf16 v[26:29], v[154:157], v[186:189], v[26:29]
	v_mfma_f32_16x16x32_bf16 v[90:93], v[134:137], v[186:189], v[90:93]
	v_mfma_f32_16x16x32_bf16 v[90:93], v[130:133], v[182:185], v[90:93]
	v_mfma_f32_16x16x32_bf16 v[82:85], v[130:133], v[190:193], v[82:85]
	v_mfma_f32_16x16x32_bf16 v[82:85], v[134:137], v[204:207], v[82:85]
	v_mfma_f32_16x16x32_bf16 v[18:21], v[154:157], v[204:207], v[18:21]
	v_mfma_f32_16x16x32_bf16 v[18:21], v[150:153], v[190:193], v[18:21]
	v_mfma_f32_16x16x32_bf16 v[10:13], v[150:153], v[208:211], v[10:13]
	v_mfma_f32_16x16x32_bf16 v[10:13], v[154:157], v[212:215], v[10:13]
	s_add_i32 s39, s39, 2
	v_mfma_f32_16x16x32_bf16 v[74:77], v[134:137], v[212:215], v[74:77]
	v_mfma_f32_16x16x32_bf16 v[74:77], v[130:133], v[208:211], v[74:77]
	s_add_u32 s33, s33, 0x100
	v_mfma_f32_16x16x32_bf16 v[86:89], v[158:161], v[174:177], v[86:89]
	v_mfma_f32_16x16x32_bf16 v[86:89], v[162:165], v[178:181], v[86:89]
	s_addc_u32 s38, s38, 0
	v_mfma_f32_16x16x32_bf16 v[22:25], v[170:173], v[178:181], v[22:25]
	v_mfma_f32_16x16x32_bf16 v[22:25], v[166:169], v[174:177], v[22:25]
	s_cmp_gt_u32 s39, 29
	v_mfma_f32_16x16x32_bf16 v[14:17], v[166:169], v[182:185], v[14:17]
	v_mfma_f32_16x16x32_bf16 v[14:17], v[170:173], v[186:189], v[14:17]
	s_mov_b64 s[0:1], s[4:5]
	v_mfma_f32_16x16x32_bf16 v[78:81], v[162:165], v[186:189], v[78:81]
	v_mfma_f32_16x16x32_bf16 v[78:81], v[158:161], v[182:185], v[78:81]
	v_mfma_f32_16x16x32_bf16 v[70:73], v[158:161], v[190:193], v[70:73]
	v_mfma_f32_16x16x32_bf16 v[70:73], v[162:165], v[204:207], v[70:73]
	v_mfma_f32_16x16x32_bf16 v[6:9], v[170:173], v[204:207], v[6:9]
	v_mfma_f32_16x16x32_bf16 v[6:9], v[166:169], v[190:193], v[6:9]
	v_mfma_f32_16x16x32_bf16 v[2:5], v[166:169], v[208:211], v[2:5]
	v_mfma_f32_16x16x32_bf16 v[2:5], v[170:173], v[212:215], v[2:5]
	v_mfma_f32_16x16x32_bf16 v[66:69], v[162:165], v[212:215], v[66:69]
	v_mfma_f32_16x16x32_bf16 v[66:69], v[158:161], v[208:211], v[66:69]
	s_setprio 0
	s_barrier
	s_cbranch_scc1 .Lpeel_exit_7

.LBB0_1440:
	s_add_u32 s46, s20, 0x100
	s_waitcnt lgkmcnt(0)
	s_addc_u32 s47, s21, 0
	s_mov_b32 s48, -2
	s_add_u32 vcc_lo, s18, 0xffea0000
	s_addc_u32 vcc_hi, s19, -1
	s_mov_b32 m0, s38
	s_nop 0
	global_load_lds_dwordx4 v210, vcc
	s_mov_b32 m0, s40
	s_nop 0
	global_load_lds_dwordx4 v212, vcc
	ds_read_b128 v[66:69], v198
	ds_read_b128 v[78:81], v198 offset:1024
	ds_read_b128 v[86:89], v198 offset:2048
	ds_read_b128 v[98:101], v198 offset:3072
	ds_read_b128 v[106:109], v198 offset:16384
	ds_read_b128 v[118:121], v198 offset:17408
	ds_read_b128 v[130:133], v198 offset:18432
	ds_read_b128 v[142:145], v198 offset:19456
	ds_read_b128 v[150:153], v234
	ds_read_b128 v[154:157], v234 offset:1024
	ds_read_b128 v[158:161], v234 offset:2048
	ds_read_b128 v[162:165], v234 offset:3072
	ds_read_b128 v[170:173], v234 offset:4096
	ds_read_b128 v[174:177], v234 offset:5120
	ds_read_b128 v[178:181], v234 offset:6144
	ds_read_b128 v[190:193], v234 offset:7168
	s_add_u32 s20, s18, 0x100
	s_addc_u32 s21, s19, 0
	s_add_i32 s49, 0, 0x10000
	s_cmpk_eq_i32 s48, 0x54
	s_cselect_b32 s25, s1, s21
	s_cselect_b32 s24, s0, s20
	s_cselect_b32 s23, s17, s47
	s_cselect_b32 s22, s16, s46
	s_add_i32 s50, 0, 0x14000
	s_add_i32 m0, s28, 0xc000
	s_nop 0
	global_load_lds_dwordx4 v210, s[18:19]
	s_add_i32 m0, s28, 0xe000
	s_nop 0
	global_load_lds_dwordx4 v212, s[18:19]
	s_waitcnt vmcnt(28)
	s_waitcnt lgkmcnt(0)
	v_mfma_f32_16x16x32_bf16 v[186:189], v[66:69], v[150:153], 0
	v_mfma_f32_16x16x32_bf16 v[186:189], v[78:81], v[154:157], v[186:189]
	s_barrier
	s_setprio 1
	v_mfma_f32_16x16x32_bf16 v[182:185], v[98:101], v[154:157], 0
	v_mfma_f32_16x16x32_bf16 v[182:185], v[86:89], v[150:153], v[182:185]
	v_mfma_f32_16x16x32_bf16 v[134:137], v[86:89], v[158:161], 0
	v_mfma_f32_16x16x32_bf16 v[134:137], v[98:101], v[162:165], v[134:137]
	v_mfma_f32_16x16x32_bf16 v[138:141], v[78:81], v[162:165], 0
	v_mfma_f32_16x16x32_bf16 v[138:141], v[66:69], v[158:161], v[138:141]
	v_mfma_f32_16x16x32_bf16 v[114:117], v[66:69], v[170:173], 0
	v_mfma_f32_16x16x32_bf16 v[114:117], v[78:81], v[174:177], v[114:117]
	v_mfma_f32_16x16x32_bf16 v[110:113], v[98:101], v[174:177], 0
	v_mfma_f32_16x16x32_bf16 v[110:113], v[86:89], v[170:173], v[110:113]
	v_mfma_f32_16x16x32_bf16 v[82:85], v[86:89], v[178:181], 0
	v_mfma_f32_16x16x32_bf16 v[82:85], v[98:101], v[190:193], v[82:85]
	v_mfma_f32_16x16x32_bf16 v[90:93], v[78:81], v[190:193], 0
	v_mfma_f32_16x16x32_bf16 v[90:93], v[66:69], v[178:181], v[90:93]
	v_mfma_f32_16x16x32_bf16 v[166:169], v[106:109], v[150:153], 0
	v_mfma_f32_16x16x32_bf16 v[166:169], v[118:121], v[154:157], v[166:169]
	v_mfma_f32_16x16x32_bf16 v[146:149], v[142:145], v[154:157], 0
	v_mfma_f32_16x16x32_bf16 v[146:149], v[130:133], v[150:153], v[146:149]
	v_mfma_f32_16x16x32_bf16 v[122:125], v[130:133], v[158:161], 0
	v_mfma_f32_16x16x32_bf16 v[122:125], v[142:145], v[162:165], v[122:125]
	v_mfma_f32_16x16x32_bf16 v[126:129], v[118:121], v[162:165], 0
	v_mfma_f32_16x16x32_bf16 v[126:129], v[106:109], v[158:161], v[126:129]
	v_mfma_f32_16x16x32_bf16 v[102:105], v[106:109], v[170:173], 0
	v_mfma_f32_16x16x32_bf16 v[102:105], v[118:121], v[174:177], v[102:105]
	v_mfma_f32_16x16x32_bf16 v[94:97], v[142:145], v[174:177], 0
	v_mfma_f32_16x16x32_bf16 v[94:97], v[130:133], v[170:173], v[94:97]
	v_mfma_f32_16x16x32_bf16 v[70:73], v[130:133], v[178:181], 0
	v_mfma_f32_16x16x32_bf16 v[70:73], v[142:145], v[190:193], v[70:73]
	v_mfma_f32_16x16x32_bf16 v[74:77], v[118:121], v[190:193], 0
	v_mfma_f32_16x16x32_bf16 v[74:77], v[106:109], v[178:181], v[74:77]
	s_setprio 0
	s_barrier
	ds_read_b128 v[150:153], v234 offset:16384
	ds_read_b128 v[154:157], v234 offset:17408
	ds_read_b128 v[158:161], v234 offset:18432
	ds_read_b128 v[162:165], v234 offset:19456
	ds_read_b128 v[170:173], v234 offset:20480
	ds_read_b128 v[174:177], v234 offset:21504
	ds_read_b128 v[178:181], v234 offset:22528
	ds_read_b128 v[190:193], v234 offset:23552
	s_add_i32 s18, s49, s26
	s_mov_b32 m0, s18
	s_nop 0
	global_load_lds_dwordx4 v194, s[22:23]
	s_add_i32 m0, s18, 0x2000
	s_add_u32 s18, s22, 0x160000
	s_addc_u32 s19, s23, 0
	s_add_i32 s49, s50, s26
	global_load_lds_dwordx4 v204, s[22:23]
	s_mov_b32 m0, s49
	s_nop 0
	global_load_lds_dwordx4 v194, s[18:19]
	s_add_i32 m0, s49, 0x2000
	s_nop 0
	global_load_lds_dwordx4 v204, s[18:19]
	s_waitcnt vmcnt(6)
	s_waitcnt lgkmcnt(0)
	v_mfma_f32_16x16x32_bf16 v[62:65], v[66:69], v[150:153], 0
	v_mfma_f32_16x16x32_bf16 v[62:65], v[78:81], v[154:157], v[62:65]
	s_barrier
	s_setprio 1
	v_mfma_f32_16x16x32_bf16 v[58:61], v[98:101], v[154:157], 0
	v_mfma_f32_16x16x32_bf16 v[58:61], v[86:89], v[150:153], v[58:61]
	v_mfma_f32_16x16x32_bf16 v[42:45], v[86:89], v[158:161], 0
	v_mfma_f32_16x16x32_bf16 v[42:45], v[98:101], v[162:165], v[42:45]
	v_mfma_f32_16x16x32_bf16 v[46:49], v[78:81], v[162:165], 0
	v_mfma_f32_16x16x32_bf16 v[46:49], v[66:69], v[158:161], v[46:49]
	v_mfma_f32_16x16x32_bf16 v[30:33], v[66:69], v[170:173], 0
	v_mfma_f32_16x16x32_bf16 v[30:33], v[78:81], v[174:177], v[30:33]
	v_mfma_f32_16x16x32_bf16 v[26:29], v[98:101], v[174:177], 0
	v_mfma_f32_16x16x32_bf16 v[26:29], v[86:89], v[170:173], v[26:29]
	v_mfma_f32_16x16x32_bf16 v[10:13], v[86:89], v[178:181], 0
	v_mfma_f32_16x16x32_bf16 v[10:13], v[98:101], v[190:193], v[10:13]
	v_mfma_f32_16x16x32_bf16 v[14:17], v[78:81], v[190:193], 0
	v_mfma_f32_16x16x32_bf16 v[14:17], v[66:69], v[178:181], v[14:17]
	v_mfma_f32_16x16x32_bf16 v[54:57], v[106:109], v[150:153], 0
	v_mfma_f32_16x16x32_bf16 v[54:57], v[118:121], v[154:157], v[54:57]
	v_mfma_f32_16x16x32_bf16 v[50:53], v[142:145], v[154:157], 0
	v_mfma_f32_16x16x32_bf16 v[50:53], v[130:133], v[150:153], v[50:53]
	v_mfma_f32_16x16x32_bf16 v[34:37], v[130:133], v[158:161], 0
	v_mfma_f32_16x16x32_bf16 v[34:37], v[142:145], v[162:165], v[34:37]
	v_mfma_f32_16x16x32_bf16 v[38:41], v[118:121], v[162:165], 0
	v_mfma_f32_16x16x32_bf16 v[38:41], v[106:109], v[158:161], v[38:41]
	v_mfma_f32_16x16x32_bf16 v[22:25], v[106:109], v[170:173], 0
	v_mfma_f32_16x16x32_bf16 v[22:25], v[118:121], v[174:177], v[22:25]
	v_mfma_f32_16x16x32_bf16 v[18:21], v[142:145], v[174:177], 0
	v_mfma_f32_16x16x32_bf16 v[18:21], v[130:133], v[170:173], v[18:21]
	v_mfma_f32_16x16x32_bf16 v[2:5], v[130:133], v[178:181], 0
	v_mfma_f32_16x16x32_bf16 v[2:5], v[142:145], v[190:193], v[2:5]
	v_mfma_f32_16x16x32_bf16 v[6:9], v[118:121], v[190:193], 0
	v_mfma_f32_16x16x32_bf16 v[6:9], v[106:109], v[178:181], v[6:9]
	s_setprio 0
	s_barrier
	s_mov_b32 m0, s28
	s_nop 0
	global_load_lds_dwordx4 v208, s[24:25]
	s_mov_b32 m0, s29
	s_nop 0
	global_load_lds_dwordx4 v206, s[24:25]
	ds_read_b128 v[66:69], v198 offset:32768
	ds_read_b128 v[78:81], v198 offset:33792
	ds_read_b128 v[86:89], v198 offset:34816
	ds_read_b128 v[98:101], v198 offset:35840
	ds_read_b128 v[106:109], v198 offset:49152
	ds_read_b128 v[118:121], v198 offset:50176
	ds_read_b128 v[130:133], v198 offset:51200
	ds_read_b128 v[142:145], v198 offset:52224
	ds_read_b128 v[150:153], v234 offset:32768
	ds_read_b128 v[154:157], v234 offset:33792
	ds_read_b128 v[158:161], v234 offset:34816
	ds_read_b128 v[162:165], v234 offset:35840
	ds_read_b128 v[170:173], v234 offset:36864
	ds_read_b128 v[174:177], v234 offset:37888
	ds_read_b128 v[178:181], v234 offset:38912
	ds_read_b128 v[190:193], v234 offset:39936
	s_add_i32 s49, 0, 0x18000
	s_add_i32 s50, 0, 0x1c000
	s_add_u32 s18, s24, 0x160000
	s_addc_u32 s19, s25, 0
	s_mov_b32 m0, s33
	s_nop 0
	global_load_lds_dwordx4 v208, s[18:19]
	s_mov_b32 m0, s37
	s_nop 0
	global_load_lds_dwordx4 v206, s[18:19]
	s_waitcnt vmcnt(8)
	s_waitcnt lgkmcnt(0)
	v_mfma_f32_16x16x32_bf16 v[186:189], v[66:69], v[150:153], v[186:189]
	v_mfma_f32_16x16x32_bf16 v[186:189], v[78:81], v[154:157], v[186:189]
	s_barrier
	s_setprio 1
	v_mfma_f32_16x16x32_bf16 v[182:185], v[98:101], v[154:157], v[182:185]
	v_mfma_f32_16x16x32_bf16 v[182:185], v[86:89], v[150:153], v[182:185]
	v_mfma_f32_16x16x32_bf16 v[134:137], v[86:89], v[158:161], v[134:137]
	v_mfma_f32_16x16x32_bf16 v[134:137], v[98:101], v[162:165], v[134:137]
	v_mfma_f32_16x16x32_bf16 v[138:141], v[78:81], v[162:165], v[138:141]
	v_mfma_f32_16x16x32_bf16 v[138:141], v[66:69], v[158:161], v[138:141]
	v_mfma_f32_16x16x32_bf16 v[114:117], v[66:69], v[170:173], v[114:117]
	v_mfma_f32_16x16x32_bf16 v[114:117], v[78:81], v[174:177], v[114:117]
	v_mfma_f32_16x16x32_bf16 v[110:113], v[98:101], v[174:177], v[110:113]
	v_mfma_f32_16x16x32_bf16 v[110:113], v[86:89], v[170:173], v[110:113]
	v_mfma_f32_16x16x32_bf16 v[82:85], v[86:89], v[178:181], v[82:85]
	v_mfma_f32_16x16x32_bf16 v[82:85], v[98:101], v[190:193], v[82:85]
	v_mfma_f32_16x16x32_bf16 v[90:93], v[78:81], v[190:193], v[90:93]
	v_mfma_f32_16x16x32_bf16 v[90:93], v[66:69], v[178:181], v[90:93]
	v_mfma_f32_16x16x32_bf16 v[166:169], v[106:109], v[150:153], v[166:169]
	v_mfma_f32_16x16x32_bf16 v[166:169], v[118:121], v[154:157], v[166:169]
	v_mfma_f32_16x16x32_bf16 v[146:149], v[142:145], v[154:157], v[146:149]
	v_mfma_f32_16x16x32_bf16 v[146:149], v[130:133], v[150:153], v[146:149]
	v_mfma_f32_16x16x32_bf16 v[122:125], v[130:133], v[158:161], v[122:125]
	v_mfma_f32_16x16x32_bf16 v[122:125], v[142:145], v[162:165], v[122:125]
	v_mfma_f32_16x16x32_bf16 v[126:129], v[118:121], v[162:165], v[126:129]
	v_mfma_f32_16x16x32_bf16 v[126:129], v[106:109], v[158:161], v[126:129]
	v_mfma_f32_16x16x32_bf16 v[102:105], v[106:109], v[170:173], v[102:105]
	v_mfma_f32_16x16x32_bf16 v[102:105], v[118:121], v[174:177], v[102:105]
	v_mfma_f32_16x16x32_bf16 v[94:97], v[142:145], v[174:177], v[94:97]
	v_mfma_f32_16x16x32_bf16 v[94:97], v[130:133], v[170:173], v[94:97]
	v_mfma_f32_16x16x32_bf16 v[70:73], v[130:133], v[178:181], v[70:73]
	v_mfma_f32_16x16x32_bf16 v[70:73], v[142:145], v[190:193], v[70:73]
	v_mfma_f32_16x16x32_bf16 v[74:77], v[118:121], v[190:193], v[74:77]
	v_mfma_f32_16x16x32_bf16 v[74:77], v[106:109], v[178:181], v[74:77]
	s_setprio 0
	s_barrier
	ds_read_b128 v[150:153], v234 offset:49152
	ds_read_b128 v[154:157], v234 offset:50176
	ds_read_b128 v[158:161], v234 offset:51200
	ds_read_b128 v[162:165], v234 offset:52224
	ds_read_b128 v[170:173], v234 offset:53248
	ds_read_b128 v[174:177], v234 offset:54272
	ds_read_b128 v[178:181], v234 offset:55296
	ds_read_b128 v[190:193], v234 offset:56320
	s_add_i32 s18, s49, s26
	s_add_u32 vcc_lo, s22, s94
	s_addc_u32 vcc_hi, s23, s95
	s_mov_b32 m0, s18
	s_nop 0
	global_load_lds_dwordx4 v194, vcc
	s_add_i32 m0, s18, 0x2000
	s_add_u32 s18, s22, 0x160080
	s_addc_u32 s19, s23, 0
	s_add_i32 s22, s50, s26
	global_load_lds_dwordx4 v204, vcc
	s_mov_b32 m0, s22
	s_nop 0
	global_load_lds_dwordx4 v194, s[18:19]
	s_add_i32 m0, s22, 0x2000
	s_nop 0
	global_load_lds_dwordx4 v204, s[18:19]
	s_waitcnt vmcnt(6)
	s_waitcnt lgkmcnt(0)
	v_mfma_f32_16x16x32_bf16 v[62:65], v[66:69], v[150:153], v[62:65]
	v_mfma_f32_16x16x32_bf16 v[62:65], v[78:81], v[154:157], v[62:65]
	s_barrier
	s_setprio 1
	v_mfma_f32_16x16x32_bf16 v[58:61], v[98:101], v[154:157], v[58:61]
	v_mfma_f32_16x16x32_bf16 v[58:61], v[86:89], v[150:153], v[58:61]
	v_mfma_f32_16x16x32_bf16 v[42:45], v[86:89], v[158:161], v[42:45]
	v_mfma_f32_16x16x32_bf16 v[42:45], v[98:101], v[162:165], v[42:45]
	v_mfma_f32_16x16x32_bf16 v[46:49], v[78:81], v[162:165], v[46:49]
	v_mfma_f32_16x16x32_bf16 v[46:49], v[66:69], v[158:161], v[46:49]
	v_mfma_f32_16x16x32_bf16 v[30:33], v[66:69], v[170:173], v[30:33]
	v_mfma_f32_16x16x32_bf16 v[30:33], v[78:81], v[174:177], v[30:33]
	v_mfma_f32_16x16x32_bf16 v[26:29], v[98:101], v[174:177], v[26:29]
	v_mfma_f32_16x16x32_bf16 v[26:29], v[86:89], v[170:173], v[26:29]
	v_mfma_f32_16x16x32_bf16 v[10:13], v[86:89], v[178:181], v[10:13]
	v_mfma_f32_16x16x32_bf16 v[10:13], v[98:101], v[190:193], v[10:13]
	s_add_i32 s48, s48, 2
	v_mfma_f32_16x16x32_bf16 v[14:17], v[78:81], v[190:193], v[14:17]
	v_mfma_f32_16x16x32_bf16 v[14:17], v[66:69], v[178:181], v[14:17]
	s_add_u32 s46, s46, 0x100
	v_mfma_f32_16x16x32_bf16 v[54:57], v[106:109], v[150:153], v[54:57]
	v_mfma_f32_16x16x32_bf16 v[54:57], v[118:121], v[154:157], v[54:57]
	s_addc_u32 s47, s47, 0
	v_mfma_f32_16x16x32_bf16 v[50:53], v[142:145], v[154:157], v[50:53]
	v_mfma_f32_16x16x32_bf16 v[50:53], v[130:133], v[150:153], v[50:53]
	s_cmpk_gt_u32 s48, 0x55
	v_mfma_f32_16x16x32_bf16 v[34:37], v[130:133], v[158:161], v[34:37]
	v_mfma_f32_16x16x32_bf16 v[34:37], v[142:145], v[162:165], v[34:37]
	s_mov_b64 s[18:19], s[20:21]
	v_mfma_f32_16x16x32_bf16 v[38:41], v[118:121], v[162:165], v[38:41]
	v_mfma_f32_16x16x32_bf16 v[38:41], v[106:109], v[158:161], v[38:41]
	v_mfma_f32_16x16x32_bf16 v[22:25], v[106:109], v[170:173], v[22:25]
	v_mfma_f32_16x16x32_bf16 v[22:25], v[118:121], v[174:177], v[22:25]
	v_mfma_f32_16x16x32_bf16 v[18:21], v[142:145], v[174:177], v[18:21]
	v_mfma_f32_16x16x32_bf16 v[18:21], v[130:133], v[170:173], v[18:21]
	v_mfma_f32_16x16x32_bf16 v[2:5], v[130:133], v[178:181], v[2:5]
	v_mfma_f32_16x16x32_bf16 v[2:5], v[142:145], v[190:193], v[2:5]
	v_mfma_f32_16x16x32_bf16 v[6:9], v[118:121], v[190:193], v[6:9]
	v_mfma_f32_16x16x32_bf16 v[6:9], v[106:109], v[178:181], v[6:9]
	s_setprio 0
	s_barrier
	s_cbranch_scc1 .Lpeel_exit_8
